# outproj K-loops reordered: LDS fragment reads right after the barrier, LDS-DMA issue spread through the MFMAs
# baseline (speedup 1.0000x reference)
.LBB0_316:
	s_and_b32 s55, s0, 0x8000
	s_add_i32 s56, s0, 0xffff8000
	v_or_b32_e32 v248, s55, v129
	v_lshl_add_u64 v[230:231], v[66:67], 0, s[38:39]
	s_and_b32 s56, s56, 0x8000
	v_readfirstlane_b32 s57, v248
	v_add_u32_e32 v249, 0x1000, v248
	v_lshl_add_u64 v[234:235], v[230:231], 0, s[10:11]
	v_add_u32_e32 v250, 0x2000, v248
	v_or_b32_e32 v146, s56, v109
	v_or_b32_e32 v147, s56, v111
	v_readfirstlane_b32 s56, v249
	s_mov_b32 m0, s57
	s_waitcnt vmcnt(0)
	s_barrier
	v_add_u32_e32 v126, v146, v110
	v_add_u32_e32 v127, v146, v108
	ds_read_b128 v[68:71], v126
	ds_read_b128 v[72:75], v127 offset:16384
	ds_read_b128 v[76:79], v127 offset:18432
	ds_read_b128 v[80:83], v127 offset:20480
	ds_read_b128 v[142:145], v126 offset:2048
	v_add_u32_e32 v141, v147, v110
	ds_read_b128 v[160:163], v127 offset:22528
	ds_read_b128 v[164:167], v127 offset:24576
	ds_read_b128 v[168:171], v127 offset:26624
	ds_read_b128 v[172:175], v127 offset:28672
	ds_read_b128 v[176:179], v127 offset:30720
	ds_read_b128 v[180:183], v141
	ds_read_b128 v[184:187], v141 offset:2048
	v_add_u32_e32 v146, v147, v108
	ds_read_b128 v[188:191], v146 offset:16384
	ds_read_b128 v[192:195], v146 offset:18432
	ds_read_b128 v[196:199], v146 offset:20480
	ds_read_b128 v[200:203], v146 offset:22528
	ds_read_b128 v[204:207], v146 offset:24576
	ds_read_b128 v[208:211], v146 offset:26624
	ds_read_b128 v[212:215], v146 offset:28672
	ds_read_b128 v[216:219], v146 offset:30720
	v_lshl_add_u64 v[236:237], v[230:231], 0, s[12:13]
	v_add_u32_e32 v251, 0x3000, v248
	v_readfirstlane_b32 s58, v250
	global_load_lds_dwordx4 v[234:235], off
	s_mov_b32 m0, s56
	v_lshl_add_u64 v[238:239], v[230:231], 0, s[14:15]
	v_or_b32_e32 v252, 0x4000, v248
	v_readfirstlane_b32 s59, v251
	global_load_lds_dwordx4 v[236:237], off
	s_waitcnt lgkmcnt(10)
	v_mfma_f32_16x16x32_bf16 v[40:43], v[68:71], v[72:75], v[40:43]
	v_mfma_f32_16x16x32_bf16 v[28:31], v[68:71], v[76:79], v[28:31]
	v_mfma_f32_16x16x32_bf16 v[60:63], v[68:71], v[80:83], v[60:63]
	v_mfma_f32_16x16x32_bf16 v[20:23], v[68:71], v[160:163], v[20:23]
	s_mov_b32 m0, s58
	v_lshl_add_u64 v[232:233], v[64:65], 0, s[38:39]
	v_lshl_add_u64 v[230:231], v[230:231], 0, s[18:19]
	v_add_u32_e32 v253, 0x5000, v248
	v_readfirstlane_b32 s60, v252
	global_load_lds_dwordx4 v[238:239], off
	v_mfma_f32_16x16x32_bf16 v[44:47], v[68:71], v[164:167], v[44:47]
	v_mfma_f32_16x16x32_bf16 v[24:27], v[68:71], v[168:171], v[24:27]
	v_mfma_f32_16x16x32_bf16 v[56:59], v[68:71], v[172:175], v[56:59]
	v_mfma_f32_16x16x32_bf16 v[12:15], v[68:71], v[176:179], v[12:15]
	s_mov_b32 m0, s59
	v_lshl_add_u64 v[240:241], v[232:233], 0, s[20:21]
	v_add_u32_e32 v254, 0x6000, v248
	v_readfirstlane_b32 s61, v253
	global_load_lds_dwordx4 v[230:231], off
	v_mfma_f32_16x16x32_bf16 v[52:55], v[142:145], v[72:75], v[52:55]
	v_mfma_f32_16x16x32_bf16 v[16:19], v[142:145], v[76:79], v[16:19]
	v_mfma_f32_16x16x32_bf16 v[48:51], v[142:145], v[80:83], v[48:51]
	v_mfma_f32_16x16x32_bf16 v[0:3], v[142:145], v[160:163], v[0:3]
	s_mov_b32 m0, s60
	v_lshl_add_u64 v[242:243], v[232:233], 0, s[22:23]
	v_add_u32_e32 v248, 0x7000, v248
	v_readfirstlane_b32 s64, v254
	global_load_lds_dwordx4 v[240:241], off
	v_mfma_f32_16x16x32_bf16 v[36:39], v[142:145], v[164:167], v[36:39]
	v_mfma_f32_16x16x32_bf16 v[8:11], v[142:145], v[168:171], v[8:11]
	v_mfma_f32_16x16x32_bf16 v[32:35], v[142:145], v[172:175], v[32:35]
	v_mfma_f32_16x16x32_bf16 v[4:7], v[142:145], v[176:179], v[4:7]
	s_mov_b32 m0, s61
	v_lshl_add_u64 v[244:245], v[232:233], 0, s[24:25]
	v_readfirstlane_b32 s65, v248
	global_load_lds_dwordx4 v[242:243], off
	s_waitcnt lgkmcnt(0)
	v_mfma_f32_16x16x32_bf16 v[40:43], v[180:183], v[188:191], v[40:43]
	v_mfma_f32_16x16x32_bf16 v[28:31], v[180:183], v[192:195], v[28:31]
	v_mfma_f32_16x16x32_bf16 v[60:63], v[180:183], v[196:199], v[60:63]
	v_mfma_f32_16x16x32_bf16 v[20:23], v[180:183], v[200:203], v[20:23]
	s_mov_b32 m0, s64
	v_lshl_add_u64 v[232:233], v[232:233], 0, s[28:29]
	global_load_lds_dwordx4 v[244:245], off
	v_mfma_f32_16x16x32_bf16 v[44:47], v[180:183], v[204:207], v[44:47]
	v_mfma_f32_16x16x32_bf16 v[24:27], v[180:183], v[208:211], v[24:27]
	v_mfma_f32_16x16x32_bf16 v[56:59], v[180:183], v[212:215], v[56:59]
	v_mfma_f32_16x16x32_bf16 v[12:15], v[180:183], v[216:219], v[12:15]
	s_mov_b32 m0, s65
	global_load_lds_dwordx4 v[232:233], off
	v_mfma_f32_16x16x32_bf16 v[52:55], v[184:187], v[188:191], v[52:55]
	v_mfma_f32_16x16x32_bf16 v[16:19], v[184:187], v[192:195], v[16:19]
	v_mfma_f32_16x16x32_bf16 v[48:51], v[184:187], v[196:199], v[48:51]
	v_mfma_f32_16x16x32_bf16 v[0:3], v[184:187], v[200:203], v[0:3]
	v_mfma_f32_16x16x32_bf16 v[36:39], v[184:187], v[204:207], v[36:39]
	v_mfma_f32_16x16x32_bf16 v[8:11], v[184:187], v[208:211], v[8:11]
	v_mfma_f32_16x16x32_bf16 v[32:35], v[184:187], v[212:215], v[32:35]
	v_mfma_f32_16x16x32_bf16 v[4:7], v[184:187], v[216:219], v[4:7]
	s_add_u32 s38, s38, 0x80
	s_addc_u32 s39, s39, 0
	s_add_i32 s0, s0, 0x8000
	s_cmpk_eq_i32 s38, 0xf80
	s_cbranch_scc0 .LBB0_316
	v_add_u32_e32 v68, s55, v109
	v_add_u32_e32 v72, v68, v110
	s_waitcnt vmcnt(0)
	s_barrier
	ds_read_b128 v[64:67], v72
	v_add_u32_e32 v126, v68, v108
	ds_read_b128 v[68:71], v126 offset:16384
	ds_read_b128 v[80:83], v126 offset:20480
	ds_read_b128 v[142:145], v126 offset:24576
	s_ashr_i32 s54, s54, 5
	s_lshl_b32 s0, s53, 7
	s_waitcnt lgkmcnt(0)
	v_mfma_f32_16x16x32_bf16 v[160:163], v[64:67], v[68:71], v[40:43]
	s_mul_hi_i32 s38, s54, 0x3000
	s_nop 1
	ds_read_b128 v[40:43], v72 offset:2048
	v_add_u32_e32 v141, 0x400, v113
	v_mfma_f32_16x16x32_bf16 v[164:167], v[64:67], v[80:83], v[60:63]
	ds_read_b128 v[72:75], v126 offset:18432
	v_mfma_f32_16x16x32_bf16 v[168:171], v[64:67], v[142:145], v[44:47]
	s_nop 2
	ds_read_b128 v[44:47], v126 offset:22528
	s_waitcnt lgkmcnt(0)
	v_mfma_f32_16x16x32_bf16 v[52:55], v[40:43], v[68:71], v[52:55]
	ds_read_b128 v[76:79], v126 offset:26624
	v_mfma_f32_16x16x32_bf16 v[80:83], v[40:43], v[80:83], v[48:51]
	ds_read_b128 v[68:71], v126 offset:28672
	s_waitcnt lgkmcnt(0)
	v_mfma_f32_16x16x32_bf16 v[56:59], v[64:67], v[68:71], v[56:59]
	ds_read_b128 v[48:51], v126 offset:30720
	v_mfma_f32_16x16x32_bf16 v[142:145], v[40:43], v[142:145], v[36:39]
	s_nop 2
	v_add_u32_e32 v36, s55, v111
	v_add_u32_e32 v37, v36, v110
	ds_read_b128 v[60:63], v37
	v_mfma_f32_16x16x32_bf16 v[172:175], v[40:43], v[68:71], v[32:35]
	v_add_u32_e32 v126, v36, v108
	s_mul_i32 s55, s54, 0x3000
	s_add_u32 s39, s50, s55
	ds_read_b128 v[32:35], v37 offset:2048
	v_mfma_f32_16x16x32_bf16 v[176:179], v[64:67], v[72:75], v[28:31]
	s_addc_u32 s56, s51, s38
	s_lshl_b32 s53, s53, 9
	s_add_u32 s38, s39, s53
	ds_read_b128 v[28:31], v126 offset:16384
	s_waitcnt lgkmcnt(0)
	v_mfma_f32_16x16x32_bf16 v[160:163], v[60:63], v[28:31], v[160:163]
	ds_read_b128 v[180:183], v126 offset:18432
	s_addc_u32 s39, s56, 0
	v_mfma_f32_16x16x32_bf16 v[28:31], v[32:35], v[28:31], v[52:55]
	ds_read_b128 v[36:39], v126 offset:20480
	s_waitcnt lgkmcnt(0)
	v_mfma_f32_16x16x32_bf16 v[164:167], v[60:63], v[36:39], v[164:167]
	ds_read_b128 v[68:71], v126 offset:22528
	v_mfma_f32_16x16x32_bf16 v[36:39], v[32:35], v[36:39], v[80:83]
	ds_read_b128 v[52:55], v126 offset:24576
	s_waitcnt lgkmcnt(0)
	v_mfma_f32_16x16x32_bf16 v[168:171], v[60:63], v[52:55], v[168:171]
	ds_read_b128 v[184:187], v126 offset:26624
	v_mfma_f32_16x16x32_bf16 v[52:55], v[32:35], v[52:55], v[142:145]
	s_nop 2
	ds_read_b128 v[142:145], v126 offset:28672
	s_waitcnt lgkmcnt(0)
	v_mfma_f32_16x16x32_bf16 v[188:191], v[60:63], v[142:145], v[56:59]
	ds_read_b128 v[80:83], v126 offset:30720
	s_barrier
	v_mfma_f32_16x16x32_bf16 v[56:59], v[32:35], v[142:145], v[172:175]
	v_mfma_f32_16x16x32_bf16 v[24:27], v[64:67], v[76:79], v[24:27]
	v_mfma_f32_16x16x32_bf16 v[16:19], v[40:43], v[72:75], v[16:19]
	v_mfma_f32_16x16x32_bf16 v[8:11], v[40:43], v[76:79], v[8:11]
	v_mfma_f32_16x16x32_bf16 v[72:75], v[60:63], v[180:183], v[176:179]
	v_mfma_f32_16x16x32_bf16 v[24:27], v[60:63], v[184:187], v[24:27]
	v_mfma_f32_16x16x32_bf16 v[16:19], v[32:35], v[180:183], v[16:19]
	v_mfma_f32_16x16x32_bf16 v[8:11], v[32:35], v[184:187], v[8:11]
	v_mfma_f32_16x16x32_bf16 v[20:23], v[64:67], v[44:47], v[20:23]
	v_mfma_f32_16x16x32_bf16 v[12:15], v[64:67], v[48:51], v[12:15]
	v_lshl_add_u64 v[64:65], s[38:39], 0, v[84:85]
	s_add_i32 s38, s54, 4
	s_add_i32 s39, s55, 0xc000
	s_mul_hi_i32 s38, s38, 0x3000
	s_add_u32 s39, s50, s39
	s_addc_u32 s56, s51, s38
	v_lshl_add_u64 v[66:67], v[64:65], 0, s[30:31]
	v_add_co_u32_e32 v64, vcc, s47, v64
	s_add_u32 s38, s39, s53
	s_nop 0
	v_addc_co_u32_e32 v65, vcc, 0, v65, vcc
	s_addc_u32 s39, s56, 0
	v_mfma_f32_16x16x32_bf16 v[20:23], v[60:63], v[68:71], v[20:23]
	s_waitcnt lgkmcnt(0)
	v_mfma_f32_16x16x32_bf16 v[12:15], v[60:63], v[80:83], v[12:15]
	ds_write2_b32 v113, v160, v72 offset1:16
	global_load_dwordx4 v[60:63], v[64:65], off
	ds_write2_b32 v113, v161, v73 offset0:128 offset1:144
	v_lshl_add_u64 v[72:73], s[38:39], 0, v[84:85]
	s_add_i32 s38, s54, 8
	s_add_i32 s39, s55, 0x18000
	s_mul_hi_i32 s38, s38, 0x3000
	s_add_u32 s39, s50, s39
	s_addc_u32 s56, s51, s38
	v_lshl_add_u64 v[126:127], v[72:73], 0, s[30:31]
	v_add_co_u32_e32 v72, vcc, s47, v72
	s_add_u32 s38, s39, s53
	s_nop 0
	v_addc_co_u32_e32 v73, vcc, 0, v73, vcc
	s_addc_u32 s39, s56, 0
	global_load_dwordx4 v[64:67], v[66:67], off offset:16
	ds_write2_b32 v141, v162, v74 offset1:16
	global_load_dwordx4 v[76:79], v[72:73], off
	ds_write2_b32 v141, v163, v75 offset0:128 offset1:144
	global_load_dwordx4 v[72:75], v[126:127], off offset:16
	v_lshl_add_u64 v[126:127], s[38:39], 0, v[84:85]
	s_add_i32 s38, s54, 12
	s_add_i32 s39, s55, 0x24000
	s_mul_hi_i32 s38, s38, 0x3000
	s_add_u32 s39, s50, s39
	s_addc_u32 s56, s51, s38
	v_lshl_add_u64 v[146:147], v[126:127], 0, s[30:31]
	v_add_co_u32_e32 v126, vcc, s47, v126
	s_add_u32 s38, s39, s53
	s_nop 0
	v_addc_co_u32_e32 v127, vcc, 0, v127, vcc
	s_addc_u32 s39, s56, 0
	ds_write2_b32 v113, v164, v20 offset0:32 offset1:48
	global_load_dwordx4 v[142:145], v[126:127], off
	ds_write2_b32 v113, v165, v21 offset0:160 offset1:176
	v_lshl_add_u64 v[20:21], s[38:39], 0, v[84:85]
	s_add_i32 s38, s54, 16
	s_add_i32 s39, s55, 0x30000
	s_mul_hi_i32 s38, s38, 0x3000
	s_add_u32 s39, s50, s39
	s_addc_u32 s56, s51, s38
	v_lshl_add_u64 v[126:127], v[20:21], 0, s[30:31]
	v_add_co_u32_e32 v20, vcc, s47, v20
	s_add_u32 s38, s39, s53
	s_nop 0
	v_addc_co_u32_e32 v21, vcc, 0, v21, vcc
	s_addc_u32 s39, s56, 0
	global_load_dwordx4 v[160:163], v[146:147], off offset:16
	ds_write2_b32 v141, v166, v22 offset0:32 offset1:48
	global_load_dwordx4 v[172:175], v[20:21], off
	ds_write2_b32 v141, v167, v23 offset0:160 offset1:176
	global_load_dwordx4 v[20:23], v[126:127], off offset:16
	v_lshl_add_u64 v[126:127], s[38:39], 0, v[84:85]
	s_add_i32 s38, s54, 20
	s_add_i32 s39, s55, 0x3c000
	s_mul_hi_i32 s38, s38, 0x3000
	s_add_u32 s39, s50, s39
	s_addc_u32 s56, s51, s38
	v_lshl_add_u64 v[146:147], v[126:127], 0, s[30:31]
	v_add_co_u32_e32 v126, vcc, s47, v126
	s_add_u32 s38, s39, s53
	s_nop 0
	v_addc_co_u32_e32 v127, vcc, 0, v127, vcc
	s_addc_u32 s39, s56, 0
	ds_write2_b32 v113, v168, v24 offset0:64 offset1:80
	global_load_dwordx4 v[164:167], v[126:127], off
	ds_write2_b32 v113, v169, v25 offset0:192 offset1:208
	v_lshl_add_u64 v[24:25], s[38:39], 0, v[84:85]
	s_add_i32 s38, s54, 24
	s_add_i32 s39, s55, 0x48000
	s_mul_hi_i32 s38, s38, 0x3000
	s_add_u32 s39, s50, s39
	s_addc_u32 s56, s51, s38
	v_lshl_add_u64 v[126:127], v[24:25], 0, s[30:31]
	v_add_co_u32_e32 v24, vcc, s47, v24
	s_add_u32 s38, s39, s53
	s_nop 0
	v_addc_co_u32_e32 v25, vcc, 0, v25, vcc
	s_addc_u32 s39, s56, 0
	s_add_i32 s54, s54, 28
	s_add_i32 s55, s55, 0x54000
	global_load_dwordx4 v[176:179], v[146:147], off offset:16
	ds_write2_b32 v141, v170, v26 offset0:64 offset1:80
	global_load_dwordx4 v[180:183], v[24:25], off
	ds_write2_b32 v141, v171, v27 offset0:192 offset1:208
	global_load_dwordx4 v[24:27], v[126:127], off offset:16
	v_lshl_add_u64 v[126:127], s[38:39], 0, v[84:85]
	s_mul_hi_i32 s38, s54, 0x3000
	s_add_u32 s39, s50, s55
	s_addc_u32 s54, s51, s38
	v_lshl_add_u64 v[146:147], v[126:127], 0, s[30:31]
	v_add_co_u32_e32 v126, vcc, s47, v126
	s_add_u32 s38, s39, s53
	s_nop 0
	v_addc_co_u32_e32 v127, vcc, 0, v127, vcc
	s_addc_u32 s39, s54, 0
	ds_write2st64_b32 v114, v188, v189 offset1:2
	global_load_dwordx4 v[168:171], v[126:127], off
	v_lshl_add_u64 v[126:127], s[38:39], 0, v[84:85]
	ds_write2st64_b32 v114, v190, v191 offset0:4 offset1:6
	global_load_dwordx4 v[184:187], v[146:147], off offset:16
	v_lshl_add_u64 v[146:147], v[126:127], 0, s[30:31]
	v_add_co_u32_e32 v126, vcc, s47, v126
	ds_write2st64_b32 v115, v12, v13 offset1:2
	s_nop 0
	v_addc_co_u32_e32 v127, vcc, 0, v127, vcc
	global_load_dwordx4 v[188:191], v[126:127], off
	ds_write2st64_b32 v115, v14, v15 offset0:4 offset1:6
	global_load_dwordx4 v[12:15], v[146:147], off offset:16
	v_mfma_f32_16x16x32_bf16 v[0:3], v[40:43], v[44:47], v[0:3]
	s_lshl_b64 s[34:35], s[34:35], 17
	s_add_i32 s52, s52, s3
	v_mfma_f32_16x16x32_bf16 v[4:7], v[40:43], v[48:51], v[4:7]
	s_add_i32 s33, s33, s46
	s_cmpk_gt_i32 s52, 0x3ff
	v_mfma_f32_16x16x32_bf16 v[68:71], v[32:35], v[68:71], v[0:3]
	s_nop 2
	v_lshl_add_u64 v[0:1], s[34:35], 0, v[90:91]
	v_or_b32_e32 v0, s0, v0
	v_lshlrev_b64 v[126:127], 2, v[0:1]
	v_lshl_add_u64 v[0:1], s[68:69], 0, v[126:127]
	v_mfma_f32_16x16x32_bf16 v[32:35], v[32:35], v[80:83], v[4:7]
	ds_read_b128 v[80:83], v112
	ds_read_b128 v[204:207], v112 offset:16
	ds_read_b128 v[200:203], v116
	ds_read_b128 v[192:195], v118 offset:16
	ds_read_b128 v[196:199], v118
	ds_read_b128 v[44:47], v117 offset:16
	ds_read_b128 v[40:43], v117
	ds_read_b128 v[48:51], v116 offset:16
	global_load_dwordx4 v[208:211], v[0:1], off offset:16 nt
	global_load_dwordx4 v[212:215], v[0:1], off nt
	s_waitcnt vmcnt(0)
	v_pk_add_f32 v[0:1], v[62:63], 0 op_sel_hi:[1,0]
	v_pk_add_f32 v[2:3], v[60:61], 0 op_sel_hi:[1,0]
	v_pk_add_f32 v[4:5], v[66:67], 0 op_sel_hi:[1,0]
	v_pk_add_f32 v[6:7], v[64:65], 0 op_sel_hi:[1,0]
	v_pk_add_f32 v[0:1], v[0:1], v[78:79]
	v_pk_add_f32 v[2:3], v[2:3], v[76:77]
	v_pk_add_f32 v[4:5], v[4:5], v[74:75]
	v_pk_add_f32 v[6:7], v[6:7], v[72:73]
	v_pk_add_f32 v[0:1], v[0:1], v[144:145]
	v_pk_add_f32 v[2:3], v[2:3], v[142:143]
	v_pk_add_f32 v[4:5], v[4:5], v[162:163]
	v_pk_add_f32 v[6:7], v[6:7], v[160:161]
	v_pk_add_f32 v[0:1], v[0:1], v[174:175]
	v_pk_add_f32 v[2:3], v[2:3], v[172:173]
	v_pk_add_f32 v[4:5], v[4:5], v[22:23]
	v_pk_add_f32 v[6:7], v[6:7], v[20:21]
	v_pk_add_f32 v[0:1], v[0:1], v[166:167]
	v_pk_add_f32 v[2:3], v[2:3], v[164:165]
	v_pk_add_f32 v[4:5], v[4:5], v[178:179]
	v_pk_add_f32 v[6:7], v[6:7], v[176:177]
	v_pk_add_f32 v[0:1], v[0:1], v[182:183]
	v_pk_add_f32 v[2:3], v[2:3], v[180:181]
	v_pk_add_f32 v[4:5], v[4:5], v[26:27]
	v_pk_add_f32 v[6:7], v[6:7], v[24:25]
	v_lshl_add_u64 v[24:25], s[48:49], 0, v[126:127]
	v_lshl_add_u64 v[26:27], s[34:35], 0, v[96:97]
	v_or_b32_e32 v26, s0, v26
	v_lshlrev_b64 v[26:27], 2, v[26:27]
	v_pk_add_f32 v[0:1], v[0:1], v[170:171]
	v_pk_add_f32 v[2:3], v[2:3], v[168:169]
	v_pk_add_f32 v[4:5], v[4:5], v[186:187]
	v_pk_add_f32 v[6:7], v[6:7], v[184:185]
	v_pk_add_f32 v[0:1], v[0:1], v[190:191]
	v_pk_add_f32 v[2:3], v[2:3], v[188:189]
	v_pk_add_f32 v[4:5], v[4:5], v[14:15]
	v_pk_add_f32 v[6:7], v[6:7], v[12:13]
	s_waitcnt lgkmcnt(6)
	v_pk_fma_f32 v[22:23], v[4:5], v[206:207], v[210:211]
	v_pk_fma_f32 v[14:15], v[0:1], v[82:83], v[214:215]
	v_pk_fma_f32 v[12:13], v[2:3], v[80:81], v[212:213]
	global_store_dwordx4 v[24:25], v[12:15], off
	v_pk_fma_f32 v[20:21], v[6:7], v[204:205], v[208:209]
	global_store_dwordx4 v[24:25], v[20:23], off offset:16
	v_lshl_add_u64 v[12:13], s[34:35], 0, v[92:93]
	v_or_b32_e32 v12, s0, v12
	v_lshlrev_b64 v[24:25], 2, v[12:13]
	v_lshl_add_u64 v[20:21], s[68:69], 0, v[24:25]
	global_load_dwordx4 v[12:15], v[20:21], off offset:16 nt
	v_lshl_add_u64 v[24:25], s[48:49], 0, v[24:25]
	global_load_dwordx4 v[20:23], v[20:21], off nt
	s_waitcnt vmcnt(1) lgkmcnt(0)
	v_pk_fma_f32 v[14:15], v[4:5], v[50:51], v[14:15]
	v_pk_fma_f32 v[12:13], v[6:7], v[48:49], v[12:13]
	global_store_dwordx4 v[24:25], v[12:15], off offset:16
	s_waitcnt vmcnt(1)
	v_pk_fma_f32 v[22:23], v[0:1], v[202:203], v[22:23]
	v_pk_fma_f32 v[20:21], v[2:3], v[200:201], v[20:21]
	v_lshl_add_u64 v[12:13], s[34:35], 0, v[94:95]
	v_or_b32_e32 v12, s0, v12
	global_store_dwordx4 v[24:25], v[20:23], off
	v_lshlrev_b64 v[24:25], 2, v[12:13]
	v_lshl_add_u64 v[48:49], s[68:69], 0, v[26:27]
	v_lshl_add_u64 v[20:21], s[68:69], 0, v[24:25]
	global_load_dwordx4 v[12:15], v[20:21], off offset:16 nt
	v_lshl_add_u64 v[24:25], s[48:49], 0, v[24:25]
	global_load_dwordx4 v[20:23], v[20:21], off nt
	v_lshl_add_u64 v[50:51], s[34:35], 0, v[100:101]
	v_or_b32_e32 v50, s0, v50
	v_lshlrev_b64 v[50:51], 2, v[50:51]
	s_waitcnt vmcnt(1)
	v_pk_fma_f32 v[14:15], v[4:5], v[46:47], v[14:15]
	v_pk_fma_f32 v[12:13], v[6:7], v[44:45], v[12:13]
	s_waitcnt vmcnt(0)
	v_pk_fma_f32 v[22:23], v[0:1], v[42:43], v[22:23]
	v_pk_fma_f32 v[20:21], v[2:3], v[40:41], v[20:21]
	global_store_dwordx4 v[24:25], v[20:23], off
	global_store_dwordx4 v[24:25], v[12:15], off offset:16
	global_load_dwordx4 v[12:15], v[48:49], off offset:16 nt
	v_lshl_add_u64 v[24:25], s[34:35], 0, v[98:99]
	global_load_dwordx4 v[20:23], v[48:49], off nt
	v_or_b32_e32 v24, s0, v24
	v_lshlrev_b64 v[48:49], 2, v[24:25]
	v_lshl_add_u64 v[24:25], s[48:49], 0, v[26:27]
	v_lshl_add_u64 v[44:45], s[68:69], 0, v[48:49]
	v_lshl_add_u64 v[48:49], s[48:49], 0, v[48:49]
	s_waitcnt vmcnt(1)
	v_pk_fma_f32 v[14:15], v[4:5], v[194:195], v[14:15]
	v_pk_fma_f32 v[12:13], v[6:7], v[192:193], v[12:13]
	s_waitcnt vmcnt(0)
	v_pk_fma_f32 v[22:23], v[0:1], v[198:199], v[22:23]
	v_pk_fma_f32 v[20:21], v[2:3], v[196:197], v[20:21]
	global_store_dwordx4 v[24:25], v[20:23], off
	global_store_dwordx4 v[24:25], v[12:15], off offset:16
	ds_write2_b32 v113, v28, v16 offset1:16
	ds_write2_b32 v113, v29, v17 offset0:128 offset1:144
	ds_write2_b32 v141, v30, v18 offset1:16
	ds_write2_b32 v141, v31, v19 offset0:128 offset1:144
	ds_write2_b32 v113, v36, v68 offset0:32 offset1:48
	ds_write2_b32 v113, v37, v69 offset0:160 offset1:176
	ds_write2_b32 v141, v38, v70 offset0:32 offset1:48
	ds_write2_b32 v141, v39, v71 offset0:160 offset1:176
	ds_write2_b32 v113, v52, v8 offset0:64 offset1:80
	ds_write2_b32 v113, v53, v9 offset0:192 offset1:208
	ds_write2_b32 v141, v54, v10 offset0:64 offset1:80
	ds_write2_b32 v141, v55, v11 offset0:192 offset1:208
	ds_write2st64_b32 v114, v56, v57 offset1:2
	ds_write2st64_b32 v114, v58, v59 offset0:4 offset1:6
	ds_write2st64_b32 v115, v32, v33 offset1:2
	ds_write2st64_b32 v115, v34, v35 offset0:4 offset1:6
	ds_read_b128 v[36:39], v112
	ds_read_b128 v[32:35], v112 offset:16
	ds_read_b128 v[28:31], v116
	ds_read_b128 v[24:27], v116 offset:16
	ds_read_b128 v[20:23], v117
	ds_read_b128 v[16:19], v117 offset:16
	ds_read_b128 v[12:15], v118
	ds_read_b128 v[8:11], v118 offset:16
	global_load_dwordx4 v[40:43], v[44:45], off offset:16 nt
	v_lshl_add_u64 v[52:53], s[68:69], 0, v[50:51]
	global_load_dwordx4 v[44:47], v[44:45], off nt
	s_waitcnt vmcnt(1) lgkmcnt(6)
	v_pk_fma_f32 v[34:35], v[4:5], v[34:35], v[42:43]
	v_pk_fma_f32 v[32:33], v[6:7], v[32:33], v[40:41]
	s_waitcnt vmcnt(0)
	v_pk_fma_f32 v[38:39], v[0:1], v[38:39], v[46:47]
	v_pk_fma_f32 v[36:37], v[2:3], v[36:37], v[44:45]
	global_store_dwordx4 v[48:49], v[36:39], off
	global_store_dwordx4 v[48:49], v[32:35], off offset:16
	global_load_dwordx4 v[32:35], v[52:53], off offset:16 nt
	v_lshl_add_u64 v[40:41], s[34:35], 0, v[102:103]
	global_load_dwordx4 v[36:39], v[52:53], off nt
	v_or_b32_e32 v40, s0, v40
	v_lshlrev_b64 v[40:41], 2, v[40:41]
	v_lshl_add_u64 v[42:43], s[48:49], 0, v[50:51]
	v_lshl_add_u64 v[44:45], s[68:69], 0, v[40:41]
	s_waitcnt vmcnt(1) lgkmcnt(4)
	v_pk_fma_f32 v[26:27], v[4:5], v[26:27], v[34:35]
	v_pk_fma_f32 v[24:25], v[6:7], v[24:25], v[32:33]
	s_waitcnt vmcnt(0)
	v_pk_fma_f32 v[30:31], v[0:1], v[30:31], v[38:39]
	v_pk_fma_f32 v[28:29], v[2:3], v[28:29], v[36:37]
	global_store_dwordx4 v[42:43], v[28:31], off
	global_store_dwordx4 v[42:43], v[24:27], off offset:16
	global_load_dwordx4 v[24:27], v[44:45], off offset:16 nt
	v_lshl_add_u64 v[32:33], s[34:35], 0, v[104:105]
	global_load_dwordx4 v[28:31], v[44:45], off nt
	v_or_b32_e32 v32, s0, v32
	v_lshlrev_b64 v[32:33], 2, v[32:33]
	v_lshl_add_u64 v[34:35], s[48:49], 0, v[40:41]
	v_lshl_add_u64 v[36:37], s[68:69], 0, v[32:33]
	s_waitcnt vmcnt(1) lgkmcnt(2)
	v_pk_fma_f32 v[18:19], v[4:5], v[18:19], v[26:27]
	v_pk_fma_f32 v[16:17], v[6:7], v[16:17], v[24:25]
	s_waitcnt vmcnt(0)
	v_pk_fma_f32 v[22:23], v[0:1], v[22:23], v[30:31]
	v_pk_fma_f32 v[20:21], v[2:3], v[20:21], v[28:29]
	global_store_dwordx4 v[34:35], v[20:23], off
	global_store_dwordx4 v[34:35], v[16:19], off offset:16
	global_load_dwordx4 v[16:19], v[36:37], off offset:16 nt
	v_lshl_add_u64 v[24:25], s[48:49], 0, v[32:33]
	global_load_dwordx4 v[20:23], v[36:37], off nt
	s_waitcnt vmcnt(0) lgkmcnt(1)
	v_pk_fma_f32 v[14:15], v[0:1], v[14:15], v[22:23]
	v_pk_fma_f32 v[12:13], v[2:3], v[12:13], v[20:21]
	s_waitcnt lgkmcnt(0)
	v_pk_fma_f32 v[2:3], v[4:5], v[10:11], v[18:19]
	v_pk_fma_f32 v[0:1], v[6:7], v[8:9], v[16:17]
	global_store_dwordx4 v[24:25], v[12:15], off
	global_store_dwordx4 v[24:25], v[0:3], off offset:16
	s_cbranch_scc0 .LBB0_315

.LBB0_687:
	s_and_b32 s40, s4, 0x8000
	s_add_i32 s41, s4, 0xffff8000
	v_or_b32_e32 v216, s40, v129
	v_lshl_add_u64 v[200:201], v[66:67], 0, s[30:31]
	s_and_b32 s41, s41, 0x8000
	v_readfirstlane_b32 s42, v216
	v_add_u32_e32 v217, 0x1000, v216
	v_lshl_add_u64 v[204:205], v[200:201], 0, s[10:11]
	v_add_u32_e32 v218, 0x2000, v216
	v_or_b32_e32 v134, s41, v101
	v_or_b32_e32 v135, s41, v103
	v_readfirstlane_b32 s41, v217
	s_mov_b32 m0, s42
	s_waitcnt vmcnt(0)
	s_barrier
	v_add_u32_e32 v126, v134, v102
	v_add_u32_e32 v127, v134, v100
	ds_read_b128 v[68:71], v126
	ds_read_b128 v[72:75], v127 offset:16384
	ds_read_b128 v[118:121], v127 offset:18432
	ds_read_b128 v[122:125], v127 offset:20480
	ds_read_b128 v[130:133], v126 offset:2048
	v_add_u32_e32 v128, v135, v102
	v_add_u32_e32 v190, v135, v100
	ds_read_b128 v[134:137], v127 offset:22528
	ds_read_b128 v[138:141], v127 offset:24576
	ds_read_b128 v[142:145], v127 offset:26624
	ds_read_b128 v[146:149], v127 offset:28672
	ds_read_b128 v[150:153], v127 offset:30720
	ds_read_b128 v[154:157], v128
	ds_read_b128 v[158:161], v128 offset:2048
	ds_read_b128 v[162:165], v190 offset:16384
	ds_read_b128 v[166:169], v190 offset:18432
	ds_read_b128 v[170:173], v190 offset:20480
	ds_read_b128 v[174:177], v190 offset:22528
	ds_read_b128 v[178:181], v190 offset:24576
	ds_read_b128 v[182:185], v190 offset:26624
	ds_read_b128 v[186:189], v190 offset:28672
	ds_read_b128 v[190:193], v190 offset:30720
	v_lshl_add_u64 v[206:207], v[200:201], 0, s[12:13]
	v_add_u32_e32 v219, 0x3000, v216
	v_readfirstlane_b32 s43, v218
	global_load_lds_dwordx4 v[204:205], off
	s_mov_b32 m0, s41
	v_lshl_add_u64 v[208:209], v[200:201], 0, s[14:15]
	v_or_b32_e32 v220, 0x4000, v216
	v_readfirstlane_b32 s44, v219
	global_load_lds_dwordx4 v[206:207], off
	s_waitcnt lgkmcnt(10)
	v_mfma_f32_16x16x32_bf16 v[44:47], v[68:71], v[72:75], v[44:47]
	v_mfma_f32_16x16x32_bf16 v[28:31], v[68:71], v[118:121], v[28:31]
	v_mfma_f32_16x16x32_bf16 v[60:63], v[68:71], v[122:125], v[60:63]
	v_mfma_f32_16x16x32_bf16 v[20:23], v[68:71], v[134:137], v[20:23]
	s_mov_b32 m0, s43
	v_lshl_add_u64 v[202:203], v[64:65], 0, s[30:31]
	v_lshl_add_u64 v[200:201], v[200:201], 0, s[16:17]
	v_add_u32_e32 v221, 0x5000, v216
	v_readfirstlane_b32 s45, v220
	global_load_lds_dwordx4 v[208:209], off
	v_mfma_f32_16x16x32_bf16 v[52:55], v[68:71], v[138:141], v[52:55]
	v_mfma_f32_16x16x32_bf16 v[24:27], v[68:71], v[142:145], v[24:27]
	v_mfma_f32_16x16x32_bf16 v[56:59], v[68:71], v[146:149], v[56:59]
	v_mfma_f32_16x16x32_bf16 v[12:15], v[68:71], v[150:153], v[12:15]
	s_mov_b32 m0, s44
	v_lshl_add_u64 v[210:211], v[202:203], 0, s[18:19]
	v_add_u32_e32 v222, 0x6000, v216
	v_readfirstlane_b32 s46, v221
	global_load_lds_dwordx4 v[200:201], off
	v_mfma_f32_16x16x32_bf16 v[48:51], v[130:133], v[72:75], v[48:51]
	v_mfma_f32_16x16x32_bf16 v[16:19], v[130:133], v[118:121], v[16:19]
	v_mfma_f32_16x16x32_bf16 v[40:43], v[130:133], v[122:125], v[40:43]
	v_mfma_f32_16x16x32_bf16 v[0:3], v[130:133], v[134:137], v[0:3]
	s_mov_b32 m0, s45
	v_lshl_add_u64 v[212:213], v[202:203], 0, s[20:21]
	v_add_u32_e32 v216, 0x7000, v216
	v_readfirstlane_b32 s47, v222
	global_load_lds_dwordx4 v[210:211], off
	v_mfma_f32_16x16x32_bf16 v[36:39], v[130:133], v[138:141], v[36:39]
	v_mfma_f32_16x16x32_bf16 v[8:11], v[130:133], v[142:145], v[8:11]
	v_mfma_f32_16x16x32_bf16 v[32:35], v[130:133], v[146:149], v[32:35]
	v_mfma_f32_16x16x32_bf16 v[4:7], v[130:133], v[150:153], v[4:7]
	s_mov_b32 m0, s46
	v_lshl_add_u64 v[214:215], v[202:203], 0, s[22:23]
	v_readfirstlane_b32 s48, v216
	global_load_lds_dwordx4 v[212:213], off
	s_waitcnt lgkmcnt(0)
	v_mfma_f32_16x16x32_bf16 v[44:47], v[154:157], v[162:165], v[44:47]
	v_mfma_f32_16x16x32_bf16 v[28:31], v[154:157], v[166:169], v[28:31]
	v_mfma_f32_16x16x32_bf16 v[60:63], v[154:157], v[170:173], v[60:63]
	v_mfma_f32_16x16x32_bf16 v[20:23], v[154:157], v[174:177], v[20:23]
	s_mov_b32 m0, s47
	v_lshl_add_u64 v[202:203], v[202:203], 0, s[24:25]
	global_load_lds_dwordx4 v[214:215], off
	v_mfma_f32_16x16x32_bf16 v[52:55], v[154:157], v[178:181], v[52:55]
	v_mfma_f32_16x16x32_bf16 v[24:27], v[154:157], v[182:185], v[24:27]
	v_mfma_f32_16x16x32_bf16 v[56:59], v[154:157], v[186:189], v[56:59]
	v_mfma_f32_16x16x32_bf16 v[12:15], v[154:157], v[190:193], v[12:15]
	s_mov_b32 m0, s48
	global_load_lds_dwordx4 v[202:203], off
	v_mfma_f32_16x16x32_bf16 v[48:51], v[158:161], v[162:165], v[48:51]
	v_mfma_f32_16x16x32_bf16 v[16:19], v[158:161], v[166:169], v[16:19]
	v_mfma_f32_16x16x32_bf16 v[40:43], v[158:161], v[170:173], v[40:43]
	v_mfma_f32_16x16x32_bf16 v[0:3], v[158:161], v[174:177], v[0:3]
	v_mfma_f32_16x16x32_bf16 v[36:39], v[158:161], v[178:181], v[36:39]
	v_mfma_f32_16x16x32_bf16 v[8:11], v[158:161], v[182:185], v[8:11]
	v_mfma_f32_16x16x32_bf16 v[32:35], v[158:161], v[186:189], v[32:35]
	v_mfma_f32_16x16x32_bf16 v[4:7], v[158:161], v[190:193], v[4:7]
	s_add_u32 s30, s30, 0x80
	s_addc_u32 s31, s31, 0
	s_add_i32 s4, s4, 0x8000
	s_cmpk_eq_i32 s30, 0xf80
	s_cbranch_scc0 .LBB0_687
	v_add_u32_e32 v68, s40, v101
	v_add_u32_e32 v69, v68, v102
	s_waitcnt vmcnt(0)
	s_barrier
	ds_read_b128 v[64:67], v69
	v_add_u32_e32 v126, v68, v100
	ds_read_b128 v[72:75], v126 offset:16384
	ds_read_b128 v[118:121], v126 offset:20480
	ds_read_b128 v[122:125], v126 offset:24576
	s_ashr_i32 s39, s39, 5
	s_mul_hi_i32 s4, s39, 0x3000
	s_waitcnt lgkmcnt(0)
	v_mfma_f32_16x16x32_bf16 v[130:133], v[64:67], v[72:75], v[44:47]
	v_add_u32_e32 v128, 0x400, v105
	s_nop 1
	ds_read_b128 v[44:47], v69 offset:2048
	v_mfma_f32_16x16x32_bf16 v[134:137], v[64:67], v[118:121], v[60:63]
	ds_read_b128 v[68:71], v126 offset:18432
	v_mfma_f32_16x16x32_bf16 v[138:141], v[64:67], v[122:125], v[52:55]
	s_nop 2
	ds_read_b128 v[52:55], v126 offset:22528
	s_waitcnt lgkmcnt(0)
	v_mfma_f32_16x16x32_bf16 v[48:51], v[44:47], v[72:75], v[48:51]
	ds_read_b128 v[72:75], v126 offset:26624
	v_mfma_f32_16x16x32_bf16 v[118:121], v[44:47], v[118:121], v[40:43]
	ds_read_b128 v[142:145], v126 offset:28672
	s_waitcnt lgkmcnt(0)
	v_mfma_f32_16x16x32_bf16 v[56:59], v[64:67], v[142:145], v[56:59]
	ds_read_b128 v[40:43], v126 offset:30720
	v_mfma_f32_16x16x32_bf16 v[122:125], v[44:47], v[122:125], v[36:39]
	s_nop 2
	v_add_u32_e32 v36, s40, v103
	v_add_u32_e32 v37, v36, v102
	ds_read_b128 v[60:63], v37
	v_mfma_f32_16x16x32_bf16 v[142:145], v[44:47], v[142:145], v[32:35]
	v_add_u32_e32 v126, v36, v100
	s_mul_i32 s40, s39, 0x3000
	s_add_u32 s30, s33, s40
	ds_read_b128 v[32:35], v37 offset:2048
	v_mfma_f32_16x16x32_bf16 v[146:149], v[64:67], v[68:71], v[28:31]
	s_addc_u32 s31, s34, s4
	s_lshl_b32 s4, s38, 9
	s_add_u32 s30, s30, s4
	ds_read_b128 v[28:31], v126 offset:16384
	s_waitcnt lgkmcnt(0)
	v_mfma_f32_16x16x32_bf16 v[130:133], v[60:63], v[28:31], v[130:133]
	ds_read_b128 v[150:153], v126 offset:18432
	s_addc_u32 s31, s31, 0
	v_mfma_f32_16x16x32_bf16 v[28:31], v[32:35], v[28:31], v[48:51]
	ds_read_b128 v[36:39], v126 offset:20480
	s_waitcnt lgkmcnt(0)
	v_mfma_f32_16x16x32_bf16 v[134:137], v[60:63], v[36:39], v[134:137]
	ds_read_b128 v[154:157], v126 offset:22528
	v_mfma_f32_16x16x32_bf16 v[36:39], v[32:35], v[36:39], v[118:121]
	ds_read_b128 v[48:51], v126 offset:24576
	s_waitcnt lgkmcnt(0)
	v_mfma_f32_16x16x32_bf16 v[118:121], v[60:63], v[48:51], v[138:141]
	s_nop 2
	ds_read_b128 v[138:141], v126 offset:26624
	v_mfma_f32_16x16x32_bf16 v[48:51], v[32:35], v[48:51], v[122:125]
	s_nop 2
	ds_read_b128 v[122:125], v126 offset:28672
	s_waitcnt lgkmcnt(0)
	v_mfma_f32_16x16x32_bf16 v[158:161], v[60:63], v[122:125], v[56:59]
	ds_read_b128 v[162:165], v126 offset:30720
	s_barrier
	v_mfma_f32_16x16x32_bf16 v[56:59], v[32:35], v[122:125], v[142:145]
	v_mfma_f32_16x16x32_bf16 v[24:27], v[64:67], v[72:75], v[24:27]
	v_mfma_f32_16x16x32_bf16 v[16:19], v[44:47], v[68:71], v[16:19]
	v_mfma_f32_16x16x32_bf16 v[8:11], v[44:47], v[72:75], v[8:11]
	v_mfma_f32_16x16x32_bf16 v[68:71], v[60:63], v[150:153], v[146:149]
	v_mfma_f32_16x16x32_bf16 v[24:27], v[60:63], v[138:141], v[24:27]
	v_mfma_f32_16x16x32_bf16 v[16:19], v[32:35], v[150:153], v[16:19]
	v_mfma_f32_16x16x32_bf16 v[8:11], v[32:35], v[138:141], v[8:11]
	v_mfma_f32_16x16x32_bf16 v[20:23], v[64:67], v[52:55], v[20:23]
	v_mfma_f32_16x16x32_bf16 v[12:15], v[64:67], v[40:43], v[12:15]
	v_lshl_add_u64 v[64:65], s[30:31], 0, v[76:77]
	s_add_i32 s30, s39, 4
	s_add_i32 s31, s40, 0xc000
	s_mul_hi_i32 s30, s30, 0x3000
	s_add_u32 s31, s33, s31
	s_addc_u32 s38, s34, s30
	v_lshl_add_u64 v[66:67], v[64:65], 0, s[26:27]
	v_add_co_u32_e32 v64, vcc, s37, v64
	s_add_u32 s30, s31, s4
	s_nop 0
	v_addc_co_u32_e32 v65, vcc, 0, v65, vcc
	s_addc_u32 s31, s38, 0
	v_mfma_f32_16x16x32_bf16 v[20:23], v[60:63], v[154:157], v[20:23]
	s_waitcnt lgkmcnt(0)
	v_mfma_f32_16x16x32_bf16 v[12:15], v[60:63], v[162:165], v[12:15]
	ds_write2_b32 v105, v130, v68 offset1:16
	global_load_dwordx4 v[60:63], v[64:65], off
	ds_write2_b32 v105, v131, v69 offset0:128 offset1:144
	v_lshl_add_u64 v[68:69], s[30:31], 0, v[76:77]
	s_add_i32 s30, s39, 8
	s_add_i32 s31, s40, 0x18000
	s_mul_hi_i32 s30, s30, 0x3000
	s_add_u32 s31, s33, s31
	s_addc_u32 s38, s34, s30
	v_lshl_add_u64 v[122:123], v[68:69], 0, s[26:27]
	v_add_co_u32_e32 v68, vcc, s37, v68
	s_add_u32 s30, s31, s4
	s_nop 0
	v_addc_co_u32_e32 v69, vcc, 0, v69, vcc
	s_addc_u32 s31, s38, 0
	global_load_dwordx4 v[64:67], v[66:67], off offset:16
	ds_write2_b32 v128, v132, v70 offset1:16
	global_load_dwordx4 v[72:75], v[68:69], off
	ds_write2_b32 v128, v133, v71 offset0:128 offset1:144
	global_load_dwordx4 v[68:71], v[122:123], off offset:16
	v_lshl_add_u64 v[122:123], s[30:31], 0, v[76:77]
	s_add_i32 s30, s39, 12
	s_add_i32 s31, s40, 0x24000
	s_mul_hi_i32 s30, s30, 0x3000
	s_add_u32 s31, s33, s31
	s_addc_u32 s38, s34, s30
	v_lshl_add_u64 v[126:127], v[122:123], 0, s[26:27]
	v_add_co_u32_e32 v122, vcc, s37, v122
	s_add_u32 s30, s31, s4
	s_nop 0
	v_addc_co_u32_e32 v123, vcc, 0, v123, vcc
	s_addc_u32 s31, s38, 0
	ds_write2_b32 v105, v134, v20 offset0:32 offset1:48
	global_load_dwordx4 v[122:125], v[122:123], off
	ds_write2_b32 v105, v135, v21 offset0:160 offset1:176
	v_lshl_add_u64 v[20:21], s[30:31], 0, v[76:77]
	s_add_i32 s30, s39, 16
	s_add_i32 s31, s40, 0x30000
	s_mul_hi_i32 s30, s30, 0x3000
	s_add_u32 s31, s33, s31
	s_addc_u32 s38, s34, s30
	global_load_dwordx4 v[130:133], v[126:127], off offset:16
	v_lshl_add_u64 v[126:127], v[20:21], 0, s[26:27]
	v_add_co_u32_e32 v20, vcc, s37, v20
	s_add_u32 s30, s31, s4
	s_nop 0
	v_addc_co_u32_e32 v21, vcc, 0, v21, vcc
	s_addc_u32 s31, s38, 0
	ds_write2_b32 v128, v136, v22 offset0:32 offset1:48
	global_load_dwordx4 v[138:141], v[20:21], off
	ds_write2_b32 v128, v137, v23 offset0:160 offset1:176
	global_load_dwordx4 v[20:23], v[126:127], off offset:16
	v_lshl_add_u64 v[126:127], s[30:31], 0, v[76:77]
	s_add_i32 s30, s39, 20
	s_add_i32 s31, s40, 0x3c000
	s_mul_hi_i32 s30, s30, 0x3000
	s_add_u32 s31, s33, s31
	s_addc_u32 s38, s34, s30
	v_lshl_add_u64 v[142:143], v[126:127], 0, s[26:27]
	v_add_co_u32_e32 v126, vcc, s37, v126
	s_add_u32 s30, s31, s4
	s_nop 0
	v_addc_co_u32_e32 v127, vcc, 0, v127, vcc
	s_addc_u32 s31, s38, 0
	ds_write2_b32 v105, v118, v24 offset0:64 offset1:80
	global_load_dwordx4 v[134:137], v[126:127], off
	ds_write2_b32 v105, v119, v25 offset0:192 offset1:208
	v_lshl_add_u64 v[24:25], s[30:31], 0, v[76:77]
	s_add_i32 s30, s39, 24
	s_add_i32 s31, s40, 0x48000
	s_mul_hi_i32 s30, s30, 0x3000
	s_add_u32 s31, s33, s31
	s_addc_u32 s38, s34, s30
	v_lshl_add_u64 v[118:119], v[24:25], 0, s[26:27]
	v_add_co_u32_e32 v24, vcc, s37, v24
	s_add_u32 s30, s31, s4
	s_nop 0
	v_addc_co_u32_e32 v25, vcc, 0, v25, vcc
	s_addc_u32 s31, s38, 0
	s_add_i32 s39, s39, 28
	s_add_i32 s40, s40, 0x54000
	global_load_dwordx4 v[142:145], v[142:143], off offset:16
	ds_write2_b32 v128, v120, v26 offset0:64 offset1:80
	global_load_dwordx4 v[146:149], v[24:25], off
	ds_write2_b32 v128, v121, v27 offset0:192 offset1:208
	global_load_dwordx4 v[24:27], v[118:119], off offset:16
	v_lshl_add_u64 v[118:119], s[30:31], 0, v[76:77]
	s_mul_hi_i32 s30, s39, 0x3000
	s_add_u32 s31, s33, s40
	s_addc_u32 s38, s34, s30
	v_lshl_add_u64 v[126:127], v[118:119], 0, s[26:27]
	v_add_co_u32_e32 v118, vcc, s37, v118
	s_add_u32 s30, s31, s4
	s_nop 0
	v_addc_co_u32_e32 v119, vcc, 0, v119, vcc
	s_addc_u32 s31, s38, 0
	ds_write2st64_b32 v106, v158, v159 offset1:2
	global_load_dwordx4 v[118:121], v[118:119], off
	ds_write2st64_b32 v106, v160, v161 offset0:4 offset1:6
	global_load_dwordx4 v[150:153], v[126:127], off offset:16
	v_lshl_add_u64 v[126:127], s[30:31], 0, v[76:77]
	v_lshl_add_u64 v[166:167], v[126:127], 0, s[26:27]
	v_add_co_u32_e32 v126, vcc, s37, v126
	ds_write2st64_b32 v107, v12, v13 offset1:2
	s_nop 0
	v_addc_co_u32_e32 v127, vcc, 0, v127, vcc
	global_load_dwordx4 v[158:161], v[126:127], off
	ds_write2st64_b32 v107, v14, v15 offset0:4 offset1:6
	global_load_dwordx4 v[12:15], v[166:167], off offset:16
	v_mfma_f32_16x16x32_bf16 v[0:3], v[44:47], v[52:55], v[0:3]
	v_lshl_add_u64 v[126:127], v[82:83], 0, s[28:29]
	v_lshl_add_u64 v[126:127], v[126:127], 0, s[4:5]
	v_mfma_f32_16x16x32_bf16 v[4:7], v[44:47], v[40:43], v[4:7]
	s_waitcnt vmcnt(0)
	v_pk_add_f32 v[62:63], v[62:63], 0 op_sel_hi:[1,0]
	v_pk_add_f32 v[60:61], v[60:61], 0 op_sel_hi:[1,0]
	v_pk_add_f32 v[66:67], v[66:67], 0 op_sel_hi:[1,0]
	v_mfma_f32_16x16x32_bf16 v[0:3], v[32:35], v[154:157], v[0:3]
	v_add_f32_e64 v64, v64, 0
	v_add_f32_e64 v65, v65, 0
	v_pk_add_f32 v[62:63], v[62:63], v[74:75]
	v_pk_add_f32 v[60:61], v[60:61], v[72:73]
	v_mfma_f32_16x16x32_bf16 v[4:7], v[32:35], v[162:165], v[4:7]
	ds_read_b128 v[32:35], v104
	ds_read_b128 v[154:157], v104 offset:16
	ds_read_b128 v[174:177], v108
	ds_read_b128 v[166:169], v110 offset:16
	ds_read_b128 v[170:173], v110
	ds_read_b128 v[52:55], v109 offset:16
	ds_read_b128 v[40:43], v109
	ds_read_b128 v[44:47], v108 offset:16
	global_load_dwordx4 v[162:165], v[126:127], off offset:16 nt
	global_load_dwordx4 v[178:181], v[126:127], off nt
	v_pk_add_f32 v[66:67], v[66:67], v[70:71]
	v_pk_add_f32 v[64:65], v[64:65], v[68:69]
	v_pk_add_f32 v[62:63], v[62:63], v[124:125]
	v_pk_add_f32 v[60:61], v[60:61], v[122:123]
	v_pk_add_f32 v[66:67], v[66:67], v[132:133]
	v_pk_add_f32 v[64:65], v[64:65], v[130:131]
	v_pk_add_f32 v[62:63], v[62:63], v[140:141]
	v_pk_add_f32 v[60:61], v[60:61], v[138:139]
	v_pk_add_f32 v[22:23], v[66:67], v[22:23]
	v_pk_add_f32 v[20:21], v[64:65], v[20:21]
	v_pk_add_f32 v[62:63], v[62:63], v[136:137]
	v_pk_add_f32 v[60:61], v[60:61], v[134:135]
	s_add_i32 s2, s2, s3
	s_add_i32 s35, s35, s36
	s_cmpk_gt_i32 s2, 0x3ff
	v_pk_add_f32 v[22:23], v[22:23], v[144:145]
	v_pk_add_f32 v[20:21], v[20:21], v[142:143]
	v_pk_add_f32 v[62:63], v[62:63], v[148:149]
	v_pk_add_f32 v[60:61], v[60:61], v[146:147]
	v_pk_add_f32 v[22:23], v[22:23], v[26:27]
	v_pk_add_f32 v[20:21], v[20:21], v[24:25]
	v_pk_add_f32 v[24:25], v[62:63], v[120:121]
	v_pk_add_f32 v[26:27], v[60:61], v[118:119]
	v_pk_add_f32 v[22:23], v[22:23], v[152:153]
	v_pk_add_f32 v[20:21], v[20:21], v[150:151]
	v_pk_add_f32 v[60:61], v[24:25], v[160:161]
	v_pk_add_f32 v[62:63], v[26:27], v[158:159]
	v_pk_add_f32 v[64:65], v[22:23], v[14:15]
	v_pk_add_f32 v[66:67], v[20:21], v[12:13]
	v_lshl_add_u64 v[26:27], v[88:89], 0, s[28:29]
	v_lshl_add_u64 v[26:27], v[26:27], 0, s[4:5]
	s_waitcnt vmcnt(1) lgkmcnt(6)
	v_pk_fma_f32 v[22:23], v[64:65], v[156:157], v[164:165]
	s_waitcnt vmcnt(0)
	v_pk_fma_f32 v[14:15], v[60:61], v[34:35], v[180:181]
	v_pk_fma_f32 v[12:13], v[62:63], v[32:33], v[178:179]
	v_pk_fma_f32 v[20:21], v[66:67], v[154:155], v[162:163]
	global_store_dwordx4 v[126:127], v[12:15], off
	global_store_dwordx4 v[126:127], v[20:23], off offset:16
	s_nop 0
	v_lshl_add_u64 v[12:13], v[84:85], 0, s[28:29]
	v_lshl_add_u64 v[24:25], v[12:13], 0, s[4:5]
	global_load_dwordx4 v[12:15], v[24:25], off offset:16 nt
	global_load_dwordx4 v[20:23], v[24:25], off nt
	s_waitcnt vmcnt(1) lgkmcnt(0)
	v_pk_fma_f32 v[14:15], v[64:65], v[46:47], v[14:15]
	v_pk_fma_f32 v[12:13], v[66:67], v[44:45], v[12:13]
	s_waitcnt vmcnt(0)
	v_pk_fma_f32 v[22:23], v[60:61], v[176:177], v[22:23]
	v_pk_fma_f32 v[20:21], v[62:63], v[174:175], v[20:21]
	global_store_dwordx4 v[24:25], v[12:15], off offset:16
	global_store_dwordx4 v[24:25], v[20:23], off
	s_nop 0
	v_lshl_add_u64 v[12:13], v[86:87], 0, s[28:29]
	v_lshl_add_u64 v[24:25], v[12:13], 0, s[4:5]
	global_load_dwordx4 v[12:15], v[24:25], off offset:16 nt
	global_load_dwordx4 v[20:23], v[24:25], off nt
	s_waitcnt vmcnt(1)
	v_pk_fma_f32 v[14:15], v[64:65], v[54:55], v[14:15]
	s_waitcnt vmcnt(0)
	v_pk_fma_f32 v[22:23], v[60:61], v[42:43], v[22:23]
	v_pk_fma_f32 v[20:21], v[62:63], v[40:41], v[20:21]
	v_pk_fma_f32 v[12:13], v[66:67], v[52:53], v[12:13]
	global_store_dwordx4 v[24:25], v[20:23], off
	global_store_dwordx4 v[24:25], v[12:15], off offset:16
	global_load_dwordx4 v[12:15], v[26:27], off offset:16 nt
	v_lshl_add_u64 v[24:25], v[90:91], 0, s[28:29]
	global_load_dwordx4 v[20:23], v[26:27], off nt
	v_lshl_add_u64 v[40:41], v[24:25], 0, s[4:5]
	v_lshl_add_u64 v[42:43], v[92:93], 0, s[28:29]
	v_lshl_add_u64 v[42:43], v[42:43], 0, s[4:5]
	s_waitcnt vmcnt(1)
	v_pk_fma_f32 v[14:15], v[64:65], v[168:169], v[14:15]
	v_pk_fma_f32 v[12:13], v[66:67], v[166:167], v[12:13]
	s_waitcnt vmcnt(0)
	v_pk_fma_f32 v[22:23], v[60:61], v[172:173], v[22:23]
	v_pk_fma_f32 v[20:21], v[62:63], v[170:171], v[20:21]
	global_store_dwordx4 v[26:27], v[20:23], off
	global_store_dwordx4 v[26:27], v[12:15], off offset:16
	ds_write2_b32 v105, v28, v16 offset1:16
	ds_write2_b32 v105, v29, v17 offset0:128 offset1:144
	ds_write2_b32 v128, v30, v18 offset1:16
	ds_write2_b32 v128, v31, v19 offset0:128 offset1:144
	ds_write2_b32 v105, v36, v0 offset0:32 offset1:48
	ds_write2_b32 v105, v37, v1 offset0:160 offset1:176
	ds_write2_b32 v128, v38, v2 offset0:32 offset1:48
	ds_write2_b32 v128, v39, v3 offset0:160 offset1:176
	ds_write2_b32 v105, v48, v8 offset0:64 offset1:80
	ds_write2_b32 v105, v49, v9 offset0:192 offset1:208
	ds_write2_b32 v128, v50, v10 offset0:64 offset1:80
	ds_write2_b32 v128, v51, v11 offset0:192 offset1:208
	ds_write2st64_b32 v106, v56, v57 offset1:2
	ds_write2st64_b32 v106, v58, v59 offset0:4 offset1:6
	ds_write2st64_b32 v107, v4, v5 offset1:2
	ds_write2st64_b32 v107, v6, v7 offset0:4 offset1:6
	ds_read_b128 v[28:31], v104
	ds_read_b128 v[24:27], v104 offset:16
	ds_read_b128 v[20:23], v108
	ds_read_b128 v[16:19], v108 offset:16
	ds_read_b128 v[12:15], v109
	ds_read_b128 v[8:11], v109 offset:16
	ds_read_b128 v[4:7], v110
	ds_read_b128 v[0:3], v110 offset:16
	global_load_dwordx4 v[32:35], v[40:41], off offset:16 nt
	global_load_dwordx4 v[36:39], v[40:41], off nt
	s_waitcnt vmcnt(1) lgkmcnt(6)
	v_pk_fma_f32 v[26:27], v[64:65], v[26:27], v[34:35]
	s_waitcnt vmcnt(0)
	v_pk_fma_f32 v[30:31], v[60:61], v[30:31], v[38:39]
	v_pk_fma_f32 v[28:29], v[62:63], v[28:29], v[36:37]
	v_pk_fma_f32 v[24:25], v[66:67], v[24:25], v[32:33]
	global_store_dwordx4 v[40:41], v[28:31], off
	global_store_dwordx4 v[40:41], v[24:27], off offset:16
	global_load_dwordx4 v[24:27], v[42:43], off offset:16 nt
	v_lshl_add_u64 v[32:33], v[94:95], 0, s[28:29]
	global_load_dwordx4 v[28:31], v[42:43], off nt
	v_lshl_add_u64 v[32:33], v[32:33], 0, s[4:5]
	s_waitcnt vmcnt(1) lgkmcnt(4)
	v_pk_fma_f32 v[18:19], v[64:65], v[18:19], v[26:27]
	v_pk_fma_f32 v[16:17], v[66:67], v[16:17], v[24:25]
	s_waitcnt vmcnt(0)
	v_pk_fma_f32 v[22:23], v[60:61], v[22:23], v[30:31]
	v_pk_fma_f32 v[20:21], v[62:63], v[20:21], v[28:29]
	global_store_dwordx4 v[42:43], v[20:23], off
	global_store_dwordx4 v[42:43], v[16:19], off offset:16
	global_load_dwordx4 v[16:19], v[32:33], off offset:16 nt
	v_lshl_add_u64 v[24:25], v[96:97], 0, s[28:29]
	global_load_dwordx4 v[20:23], v[32:33], off nt
	v_lshl_add_u64 v[24:25], v[24:25], 0, s[4:5]
	s_waitcnt vmcnt(1) lgkmcnt(2)
	v_pk_fma_f32 v[10:11], v[64:65], v[10:11], v[18:19]
	v_pk_fma_f32 v[8:9], v[66:67], v[8:9], v[16:17]
	s_waitcnt vmcnt(0)
	v_pk_fma_f32 v[14:15], v[60:61], v[14:15], v[22:23]
	v_pk_fma_f32 v[12:13], v[62:63], v[12:13], v[20:21]
	global_store_dwordx4 v[32:33], v[12:15], off
	global_store_dwordx4 v[32:33], v[8:11], off offset:16
	global_load_dwordx4 v[8:11], v[24:25], off offset:16 nt
	s_waitcnt vmcnt(0) lgkmcnt(0)
	v_pk_fma_f32 v[2:3], v[64:65], v[2:3], v[10:11]
	global_load_dwordx4 v[12:15], v[24:25], off nt
	v_pk_fma_f32 v[0:1], v[66:67], v[0:1], v[8:9]
	global_store_dwordx4 v[24:25], v[0:3], off offset:16
	s_waitcnt vmcnt(1)
	v_pk_fma_f32 v[6:7], v[60:61], v[6:7], v[14:15]
	v_pk_fma_f32 v[4:5], v[62:63], v[4:5], v[12:13]
	global_store_dwordx4 v[24:25], v[4:7], off
	s_cbranch_scc0 .LBB0_686
